# scan: load waits no longer drain the CT stores (counted vmcnt incl. 8 younger stores, full drain at unit entry), 4 v-quarter units of one head share an XCD; GEMM loop heads 64B aligned
# speedup vs baseline: 1.0223x; 1.0002x over previous
.LBB0_176:
	s_ashr_i32 s19, s18, 31
	s_lshl_b64 s[20:21], s[18:19], 21
	s_add_u32 s20, s54, s20
	s_addc_u32 s21, s55, s21
	s_and_b64 s[22:23], s[0:1], exec
	s_cselect_b32 s19, s21, s27
	s_cselect_b32 s58, s20, s26
	s_ashr_i32 s17, s16, 31
	s_lshl_b64 s[22:23], s[16:17], 21
	s_add_u32 s22, s35, s22
	s_addc_u32 s23, s39, s23
	s_and_b64 s[30:31], s[0:1], exec
	s_cselect_b32 s17, s23, s29
	s_cselect_b32 s59, s22, s28
	s_add_u32 s26, s26, 0x100080
	s_addc_u32 s27, s27, 0
	s_add_u32 s62, s28, 0x100
	v_mov_b32_e32 v2, 0
	s_addc_u32 s63, s29, 0
	s_mov_b32 s80, -2
	v_mov_b32_e32 v3, v2
	v_mov_b32_e32 v4, v2
	v_mov_b32_e32 v5, v2
	v_mov_b32_e32 v6, v2
	v_mov_b32_e32 v7, v2
	v_mov_b32_e32 v8, v2
	v_mov_b32_e32 v9, v2
	v_mov_b32_e32 v10, v2
	v_mov_b32_e32 v11, v2
	v_mov_b32_e32 v12, v2
	v_mov_b32_e32 v13, v2
	v_mov_b32_e32 v18, v2
	v_mov_b32_e32 v19, v2
	v_mov_b32_e32 v20, v2
	v_mov_b32_e32 v21, v2
	v_mov_b32_e32 v26, v2
	v_mov_b32_e32 v27, v2
	v_mov_b32_e32 v28, v2
	v_mov_b32_e32 v29, v2
	v_mov_b32_e32 v34, v2
	v_mov_b32_e32 v35, v2
	v_mov_b32_e32 v36, v2
	v_mov_b32_e32 v37, v2
	v_mov_b32_e32 v42, v2
	v_mov_b32_e32 v43, v2
	v_mov_b32_e32 v44, v2
	v_mov_b32_e32 v45, v2
	v_mov_b32_e32 v50, v2
	v_mov_b32_e32 v51, v2
	v_mov_b32_e32 v52, v2
	v_mov_b32_e32 v53, v2
	v_mov_b32_e32 v14, v2
	v_mov_b32_e32 v15, v2
	v_mov_b32_e32 v16, v2
	v_mov_b32_e32 v17, v2
	v_mov_b32_e32 v22, v2
	v_mov_b32_e32 v23, v2
	v_mov_b32_e32 v24, v2
	v_mov_b32_e32 v25, v2
	v_mov_b32_e32 v30, v2
	v_mov_b32_e32 v31, v2
	v_mov_b32_e32 v32, v2
	v_mov_b32_e32 v33, v2
	v_mov_b32_e32 v38, v2
	v_mov_b32_e32 v39, v2
	v_mov_b32_e32 v40, v2
	v_mov_b32_e32 v41, v2
	v_mov_b32_e32 v46, v2
	v_mov_b32_e32 v47, v2
	v_mov_b32_e32 v48, v2
	v_mov_b32_e32 v49, v2
	v_mov_b32_e32 v54, v2
	v_mov_b32_e32 v55, v2
	v_mov_b32_e32 v56, v2
	v_mov_b32_e32 v57, v2
	v_mov_b32_e32 v58, v2
	v_mov_b32_e32 v59, v2
	v_mov_b32_e32 v60, v2
	v_mov_b32_e32 v61, v2
	v_mov_b32_e32 v62, v2
	v_mov_b32_e32 v63, v2
	v_mov_b32_e32 v64, v2
	v_mov_b32_e32 v65, v2
	v_mov_b32_e32 v66, v2
	v_mov_b32_e32 v67, v2
	v_mov_b32_e32 v68, v2
	v_mov_b32_e32 v69, v2
	v_mov_b32_e32 v70, v2
	v_mov_b32_e32 v71, v2
	v_mov_b32_e32 v72, v2
	v_mov_b32_e32 v73, v2
	v_mov_b32_e32 v74, v2
	v_mov_b32_e32 v75, v2
	v_mov_b32_e32 v76, v2
	v_mov_b32_e32 v77, v2
	v_mov_b32_e32 v82, v2
	v_mov_b32_e32 v83, v2
	v_mov_b32_e32 v84, v2
	v_mov_b32_e32 v85, v2
	v_mov_b32_e32 v90, v2
	v_mov_b32_e32 v91, v2
	v_mov_b32_e32 v92, v2
	v_mov_b32_e32 v93, v2
	v_mov_b32_e32 v98, v2
	v_mov_b32_e32 v99, v2
	v_mov_b32_e32 v100, v2
	v_mov_b32_e32 v101, v2
	v_mov_b32_e32 v106, v2
	v_mov_b32_e32 v107, v2
	v_mov_b32_e32 v108, v2
	v_mov_b32_e32 v109, v2
	v_mov_b32_e32 v114, v2
	v_mov_b32_e32 v115, v2
	v_mov_b32_e32 v116, v2
	v_mov_b32_e32 v117, v2
	v_mov_b32_e32 v78, v2
	v_mov_b32_e32 v79, v2
	v_mov_b32_e32 v80, v2
	v_mov_b32_e32 v81, v2
	v_mov_b32_e32 v86, v2
	v_mov_b32_e32 v87, v2
	v_mov_b32_e32 v88, v2
	v_mov_b32_e32 v89, v2
	v_mov_b32_e32 v94, v2
	v_mov_b32_e32 v95, v2
	v_mov_b32_e32 v96, v2
	v_mov_b32_e32 v97, v2
	v_mov_b32_e32 v102, v2
	v_mov_b32_e32 v103, v2
	v_mov_b32_e32 v104, v2
	v_mov_b32_e32 v105, v2
	v_mov_b32_e32 v110, v2
	v_mov_b32_e32 v111, v2
	v_mov_b32_e32 v112, v2
	v_mov_b32_e32 v113, v2
	v_mov_b32_e32 v118, v2
	v_mov_b32_e32 v119, v2
	v_mov_b32_e32 v120, v2
	v_mov_b32_e32 v121, v2
	v_mov_b32_e32 v122, v2
	v_mov_b32_e32 v123, v2
	v_mov_b32_e32 v124, v2
	v_mov_b32_e32 v125, v2
	v_mov_b32_e32 v126, v2
	v_mov_b32_e32 v127, v2
	v_mov_b32_e32 v128, v2
	v_mov_b32_e32 v129, v2
	s_setprio 0
	.p2align 6

.LBB0_196:
	s_ashr_i32 s21, s20, 31
	s_lshl_b64 s[22:23], s[20:21], 21
	s_add_u32 s22, s54, s22
	s_addc_u32 s23, s55, s23
	s_and_b64 s[24:25], s[0:1], exec
	s_cselect_b32 s21, s23, s29
	s_cselect_b32 s63, s22, s28
	s_ashr_i32 s19, s18, 31
	s_lshl_b64 s[24:25], s[18:19], 21
	s_add_u32 s24, s44, s24
	s_addc_u32 s25, s45, s25
	s_and_b64 s[34:35], s[0:1], exec
	s_cselect_b32 s19, s25, s31
	s_cselect_b32 s80, s24, s30
	s_add_u32 s28, s28, 0x100080
	s_addc_u32 s29, s29, 0
	s_add_u32 s81, s30, 0x100
	v_mov_b32_e32 v2, 0
	s_addc_u32 s82, s31, 0
	s_mov_b32 s83, -2
	v_mov_b32_e32 v3, v2
	v_mov_b32_e32 v4, v2
	v_mov_b32_e32 v5, v2
	v_mov_b32_e32 v6, v2
	v_mov_b32_e32 v7, v2
	v_mov_b32_e32 v8, v2
	v_mov_b32_e32 v9, v2
	v_mov_b32_e32 v18, v2
	v_mov_b32_e32 v19, v2
	v_mov_b32_e32 v20, v2
	v_mov_b32_e32 v21, v2
	v_mov_b32_e32 v22, v2
	v_mov_b32_e32 v23, v2
	v_mov_b32_e32 v24, v2
	v_mov_b32_e32 v25, v2
	v_mov_b32_e32 v34, v2
	v_mov_b32_e32 v35, v2
	v_mov_b32_e32 v36, v2
	v_mov_b32_e32 v37, v2
	v_mov_b32_e32 v38, v2
	v_mov_b32_e32 v39, v2
	v_mov_b32_e32 v40, v2
	v_mov_b32_e32 v41, v2
	v_mov_b32_e32 v50, v2
	v_mov_b32_e32 v51, v2
	v_mov_b32_e32 v52, v2
	v_mov_b32_e32 v53, v2
	v_mov_b32_e32 v54, v2
	v_mov_b32_e32 v55, v2
	v_mov_b32_e32 v56, v2
	v_mov_b32_e32 v57, v2
	v_mov_b32_e32 v10, v2
	v_mov_b32_e32 v11, v2
	v_mov_b32_e32 v12, v2
	v_mov_b32_e32 v13, v2
	v_mov_b32_e32 v14, v2
	v_mov_b32_e32 v15, v2
	v_mov_b32_e32 v16, v2
	v_mov_b32_e32 v17, v2
	v_mov_b32_e32 v26, v2
	v_mov_b32_e32 v27, v2
	v_mov_b32_e32 v28, v2
	v_mov_b32_e32 v29, v2
	v_mov_b32_e32 v30, v2
	v_mov_b32_e32 v31, v2
	v_mov_b32_e32 v32, v2
	v_mov_b32_e32 v33, v2
	v_mov_b32_e32 v42, v2
	v_mov_b32_e32 v43, v2
	v_mov_b32_e32 v44, v2
	v_mov_b32_e32 v45, v2
	v_mov_b32_e32 v46, v2
	v_mov_b32_e32 v47, v2
	v_mov_b32_e32 v48, v2
	v_mov_b32_e32 v49, v2
	v_mov_b32_e32 v58, v2
	v_mov_b32_e32 v59, v2
	v_mov_b32_e32 v60, v2
	v_mov_b32_e32 v61, v2
	v_mov_b32_e32 v62, v2
	v_mov_b32_e32 v63, v2
	v_mov_b32_e32 v64, v2
	v_mov_b32_e32 v65, v2
	v_mov_b32_e32 v66, v2
	v_mov_b32_e32 v67, v2
	v_mov_b32_e32 v68, v2
	v_mov_b32_e32 v69, v2
	v_mov_b32_e32 v70, v2
	v_mov_b32_e32 v71, v2
	v_mov_b32_e32 v72, v2
	v_mov_b32_e32 v73, v2
	v_mov_b32_e32 v82, v2
	v_mov_b32_e32 v83, v2
	v_mov_b32_e32 v84, v2
	v_mov_b32_e32 v85, v2
	v_mov_b32_e32 v86, v2
	v_mov_b32_e32 v87, v2
	v_mov_b32_e32 v88, v2
	v_mov_b32_e32 v89, v2
	v_mov_b32_e32 v98, v2
	v_mov_b32_e32 v99, v2
	v_mov_b32_e32 v100, v2
	v_mov_b32_e32 v101, v2
	v_mov_b32_e32 v102, v2
	v_mov_b32_e32 v103, v2
	v_mov_b32_e32 v104, v2
	v_mov_b32_e32 v105, v2
	v_mov_b32_e32 v114, v2
	v_mov_b32_e32 v115, v2
	v_mov_b32_e32 v116, v2
	v_mov_b32_e32 v117, v2
	v_mov_b32_e32 v118, v2
	v_mov_b32_e32 v119, v2
	v_mov_b32_e32 v120, v2
	v_mov_b32_e32 v121, v2
	v_mov_b32_e32 v74, v2
	v_mov_b32_e32 v75, v2
	v_mov_b32_e32 v76, v2
	v_mov_b32_e32 v77, v2
	v_mov_b32_e32 v78, v2
	v_mov_b32_e32 v79, v2
	v_mov_b32_e32 v80, v2
	v_mov_b32_e32 v81, v2
	v_mov_b32_e32 v90, v2
	v_mov_b32_e32 v91, v2
	v_mov_b32_e32 v92, v2
	v_mov_b32_e32 v93, v2
	v_mov_b32_e32 v94, v2
	v_mov_b32_e32 v95, v2
	v_mov_b32_e32 v96, v2
	v_mov_b32_e32 v97, v2
	v_mov_b32_e32 v106, v2
	v_mov_b32_e32 v107, v2
	v_mov_b32_e32 v108, v2
	v_mov_b32_e32 v109, v2
	v_mov_b32_e32 v110, v2
	v_mov_b32_e32 v111, v2
	v_mov_b32_e32 v112, v2
	v_mov_b32_e32 v113, v2
	v_mov_b32_e32 v122, v2
	v_mov_b32_e32 v123, v2
	v_mov_b32_e32 v124, v2
	v_mov_b32_e32 v125, v2
	v_mov_b32_e32 v126, v2
	v_mov_b32_e32 v127, v2
	v_mov_b32_e32 v128, v2
	v_mov_b32_e32 v129, v2
	s_setprio 0
	.p2align 6

.LBB0_216:
	s_ashr_i32 s21, s20, 31
	s_lshl_b64 s[22:23], s[20:21], 21
	s_add_u32 s22, s54, s22
	s_addc_u32 s23, s55, s23
	s_and_b64 s[24:25], s[0:1], exec
	s_cselect_b32 s21, s23, s29
	s_cselect_b32 s63, s22, s28
	s_ashr_i32 s19, s18, 31
	s_lshl_b64 s[24:25], s[18:19], 21
	s_add_u32 s24, s44, s24
	s_addc_u32 s25, s45, s25
	s_and_b64 s[34:35], s[0:1], exec
	s_cselect_b32 s19, s25, s31
	s_cselect_b32 s80, s24, s30
	s_add_u32 s28, s28, 0x100080
	s_addc_u32 s29, s29, 0
	s_add_u32 s81, s30, 0x100
	v_mov_b32_e32 v2, 0
	s_addc_u32 s82, s31, 0
	s_mov_b32 s83, -2
	v_mov_b32_e32 v3, v2
	v_mov_b32_e32 v4, v2
	v_mov_b32_e32 v5, v2
	v_mov_b32_e32 v6, v2
	v_mov_b32_e32 v7, v2
	v_mov_b32_e32 v8, v2
	v_mov_b32_e32 v9, v2
	v_mov_b32_e32 v10, v2
	v_mov_b32_e32 v11, v2
	v_mov_b32_e32 v12, v2
	v_mov_b32_e32 v13, v2
	v_mov_b32_e32 v18, v2
	v_mov_b32_e32 v19, v2
	v_mov_b32_e32 v20, v2
	v_mov_b32_e32 v21, v2
	v_mov_b32_e32 v26, v2
	v_mov_b32_e32 v27, v2
	v_mov_b32_e32 v28, v2
	v_mov_b32_e32 v29, v2
	v_mov_b32_e32 v34, v2
	v_mov_b32_e32 v35, v2
	v_mov_b32_e32 v36, v2
	v_mov_b32_e32 v37, v2
	v_mov_b32_e32 v42, v2
	v_mov_b32_e32 v43, v2
	v_mov_b32_e32 v44, v2
	v_mov_b32_e32 v45, v2
	v_mov_b32_e32 v50, v2
	v_mov_b32_e32 v51, v2
	v_mov_b32_e32 v52, v2
	v_mov_b32_e32 v53, v2
	v_mov_b32_e32 v14, v2
	v_mov_b32_e32 v15, v2
	v_mov_b32_e32 v16, v2
	v_mov_b32_e32 v17, v2
	v_mov_b32_e32 v22, v2
	v_mov_b32_e32 v23, v2
	v_mov_b32_e32 v24, v2
	v_mov_b32_e32 v25, v2
	v_mov_b32_e32 v30, v2
	v_mov_b32_e32 v31, v2
	v_mov_b32_e32 v32, v2
	v_mov_b32_e32 v33, v2
	v_mov_b32_e32 v38, v2
	v_mov_b32_e32 v39, v2
	v_mov_b32_e32 v40, v2
	v_mov_b32_e32 v41, v2
	v_mov_b32_e32 v46, v2
	v_mov_b32_e32 v47, v2
	v_mov_b32_e32 v48, v2
	v_mov_b32_e32 v49, v2
	v_mov_b32_e32 v54, v2
	v_mov_b32_e32 v55, v2
	v_mov_b32_e32 v56, v2
	v_mov_b32_e32 v57, v2
	v_mov_b32_e32 v58, v2
	v_mov_b32_e32 v59, v2
	v_mov_b32_e32 v60, v2
	v_mov_b32_e32 v61, v2
	v_mov_b32_e32 v62, v2
	v_mov_b32_e32 v63, v2
	v_mov_b32_e32 v64, v2
	v_mov_b32_e32 v65, v2
	v_mov_b32_e32 v66, v2
	v_mov_b32_e32 v67, v2
	v_mov_b32_e32 v68, v2
	v_mov_b32_e32 v69, v2
	v_mov_b32_e32 v70, v2
	v_mov_b32_e32 v71, v2
	v_mov_b32_e32 v72, v2
	v_mov_b32_e32 v73, v2
	v_mov_b32_e32 v74, v2
	v_mov_b32_e32 v75, v2
	v_mov_b32_e32 v76, v2
	v_mov_b32_e32 v77, v2
	v_mov_b32_e32 v82, v2
	v_mov_b32_e32 v83, v2
	v_mov_b32_e32 v84, v2
	v_mov_b32_e32 v85, v2
	v_mov_b32_e32 v90, v2
	v_mov_b32_e32 v91, v2
	v_mov_b32_e32 v92, v2
	v_mov_b32_e32 v93, v2
	v_mov_b32_e32 v98, v2
	v_mov_b32_e32 v99, v2
	v_mov_b32_e32 v100, v2
	v_mov_b32_e32 v101, v2
	v_mov_b32_e32 v106, v2
	v_mov_b32_e32 v107, v2
	v_mov_b32_e32 v108, v2
	v_mov_b32_e32 v109, v2
	v_mov_b32_e32 v114, v2
	v_mov_b32_e32 v115, v2
	v_mov_b32_e32 v116, v2
	v_mov_b32_e32 v117, v2
	v_mov_b32_e32 v78, v2
	v_mov_b32_e32 v79, v2
	v_mov_b32_e32 v80, v2
	v_mov_b32_e32 v81, v2
	v_mov_b32_e32 v86, v2
	v_mov_b32_e32 v87, v2
	v_mov_b32_e32 v88, v2
	v_mov_b32_e32 v89, v2
	v_mov_b32_e32 v94, v2
	v_mov_b32_e32 v95, v2
	v_mov_b32_e32 v96, v2
	v_mov_b32_e32 v97, v2
	v_mov_b32_e32 v102, v2
	v_mov_b32_e32 v103, v2
	v_mov_b32_e32 v104, v2
	v_mov_b32_e32 v105, v2
	v_mov_b32_e32 v110, v2
	v_mov_b32_e32 v111, v2
	v_mov_b32_e32 v112, v2
	v_mov_b32_e32 v113, v2
	v_mov_b32_e32 v118, v2
	v_mov_b32_e32 v119, v2
	v_mov_b32_e32 v120, v2
	v_mov_b32_e32 v121, v2
	v_mov_b32_e32 v122, v2
	v_mov_b32_e32 v123, v2
	v_mov_b32_e32 v124, v2
	v_mov_b32_e32 v125, v2
	v_mov_b32_e32 v126, v2
	v_mov_b32_e32 v127, v2
	v_mov_b32_e32 v128, v2
	v_mov_b32_e32 v129, v2
	s_setprio 0
	.p2align 6

.LBB0_236:
	s_ashr_i32 s19, s18, 31
	s_lshl_b64 s[20:21], s[18:19], 21
	s_add_u32 s20, s54, s20
	s_addc_u32 s21, s55, s21
	s_and_b64 s[22:23], s[0:1], exec
	s_cselect_b32 s19, s21, s27
	s_cselect_b32 s53, s20, s26
	s_ashr_i32 s17, s16, 31
	s_lshl_b64 s[22:23], s[16:17], 21
	s_add_u32 s22, s35, s22
	s_addc_u32 s23, s43, s23
	s_and_b64 s[30:31], s[0:1], exec
	s_cselect_b32 s17, s23, s29
	s_cselect_b32 s58, s22, s28
	s_add_u32 s26, s26, 0x100080
	s_addc_u32 s27, s27, 0
	s_add_u32 s59, s28, 0x100
	v_mov_b32_e32 v2, 0
	s_addc_u32 s62, s29, 0
	s_mov_b32 s63, -2
	v_mov_b32_e32 v3, v2
	v_mov_b32_e32 v4, v2
	v_mov_b32_e32 v5, v2
	v_mov_b32_e32 v6, v2
	v_mov_b32_e32 v7, v2
	v_mov_b32_e32 v8, v2
	v_mov_b32_e32 v9, v2
	v_mov_b32_e32 v18, v2
	v_mov_b32_e32 v19, v2
	v_mov_b32_e32 v20, v2
	v_mov_b32_e32 v21, v2
	v_mov_b32_e32 v22, v2
	v_mov_b32_e32 v23, v2
	v_mov_b32_e32 v24, v2
	v_mov_b32_e32 v25, v2
	v_mov_b32_e32 v34, v2
	v_mov_b32_e32 v35, v2
	v_mov_b32_e32 v36, v2
	v_mov_b32_e32 v37, v2
	v_mov_b32_e32 v38, v2
	v_mov_b32_e32 v39, v2
	v_mov_b32_e32 v40, v2
	v_mov_b32_e32 v41, v2
	v_mov_b32_e32 v50, v2
	v_mov_b32_e32 v51, v2
	v_mov_b32_e32 v52, v2
	v_mov_b32_e32 v53, v2
	v_mov_b32_e32 v54, v2
	v_mov_b32_e32 v55, v2
	v_mov_b32_e32 v56, v2
	v_mov_b32_e32 v57, v2
	v_mov_b32_e32 v10, v2
	v_mov_b32_e32 v11, v2
	v_mov_b32_e32 v12, v2
	v_mov_b32_e32 v13, v2
	v_mov_b32_e32 v14, v2
	v_mov_b32_e32 v15, v2
	v_mov_b32_e32 v16, v2
	v_mov_b32_e32 v17, v2
	v_mov_b32_e32 v26, v2
	v_mov_b32_e32 v27, v2
	v_mov_b32_e32 v28, v2
	v_mov_b32_e32 v29, v2
	v_mov_b32_e32 v30, v2
	v_mov_b32_e32 v31, v2
	v_mov_b32_e32 v32, v2
	v_mov_b32_e32 v33, v2
	v_mov_b32_e32 v42, v2
	v_mov_b32_e32 v43, v2
	v_mov_b32_e32 v44, v2
	v_mov_b32_e32 v45, v2
	v_mov_b32_e32 v46, v2
	v_mov_b32_e32 v47, v2
	v_mov_b32_e32 v48, v2
	v_mov_b32_e32 v49, v2
	v_mov_b32_e32 v58, v2
	v_mov_b32_e32 v59, v2
	v_mov_b32_e32 v60, v2
	v_mov_b32_e32 v61, v2
	v_mov_b32_e32 v62, v2
	v_mov_b32_e32 v63, v2
	v_mov_b32_e32 v64, v2
	v_mov_b32_e32 v65, v2
	v_mov_b32_e32 v66, v2
	v_mov_b32_e32 v67, v2
	v_mov_b32_e32 v68, v2
	v_mov_b32_e32 v69, v2
	v_mov_b32_e32 v70, v2
	v_mov_b32_e32 v71, v2
	v_mov_b32_e32 v72, v2
	v_mov_b32_e32 v73, v2
	v_mov_b32_e32 v82, v2
	v_mov_b32_e32 v83, v2
	v_mov_b32_e32 v84, v2
	v_mov_b32_e32 v85, v2
	v_mov_b32_e32 v86, v2
	v_mov_b32_e32 v87, v2
	v_mov_b32_e32 v88, v2
	v_mov_b32_e32 v89, v2
	v_mov_b32_e32 v98, v2
	v_mov_b32_e32 v99, v2
	v_mov_b32_e32 v100, v2
	v_mov_b32_e32 v101, v2
	v_mov_b32_e32 v102, v2
	v_mov_b32_e32 v103, v2
	v_mov_b32_e32 v104, v2
	v_mov_b32_e32 v105, v2
	v_mov_b32_e32 v114, v2
	v_mov_b32_e32 v115, v2
	v_mov_b32_e32 v116, v2
	v_mov_b32_e32 v117, v2
	v_mov_b32_e32 v118, v2
	v_mov_b32_e32 v119, v2
	v_mov_b32_e32 v120, v2
	v_mov_b32_e32 v121, v2
	v_mov_b32_e32 v74, v2
	v_mov_b32_e32 v75, v2
	v_mov_b32_e32 v76, v2
	v_mov_b32_e32 v77, v2
	v_mov_b32_e32 v78, v2
	v_mov_b32_e32 v79, v2
	v_mov_b32_e32 v80, v2
	v_mov_b32_e32 v81, v2
	v_mov_b32_e32 v90, v2
	v_mov_b32_e32 v91, v2
	v_mov_b32_e32 v92, v2
	v_mov_b32_e32 v93, v2
	v_mov_b32_e32 v94, v2
	v_mov_b32_e32 v95, v2
	v_mov_b32_e32 v96, v2
	v_mov_b32_e32 v97, v2
	v_mov_b32_e32 v106, v2
	v_mov_b32_e32 v107, v2
	v_mov_b32_e32 v108, v2
	v_mov_b32_e32 v109, v2
	v_mov_b32_e32 v110, v2
	v_mov_b32_e32 v111, v2
	v_mov_b32_e32 v112, v2
	v_mov_b32_e32 v113, v2
	v_mov_b32_e32 v122, v2
	v_mov_b32_e32 v123, v2
	v_mov_b32_e32 v124, v2
	v_mov_b32_e32 v125, v2
	v_mov_b32_e32 v126, v2
	v_mov_b32_e32 v127, v2
	v_mov_b32_e32 v128, v2
	v_mov_b32_e32 v129, v2
	s_setprio 0
	.p2align 6

.LBB0_268:
	s_or_b64 exec, exec, s[30:31]
	v_ashrrev_i32_e32 v147, 31, v146
	v_lshlrev_b64 v[6:7], 21, v[146:147]
	v_ashrrev_i32_e32 v145, 31, v144
	v_lshl_add_u64 v[148:149], s[0:1], 0, v[6:7]
	v_lshlrev_b64 v[6:7], 21, v[144:145]
	v_lshl_add_u64 v[150:151], s[54:55], 0, v[6:7]
	v_cndmask_b32_e64 v154, v2, v150, s[28:29]
	v_lshl_add_u64 v[158:159], v[2:3], 0, s[22:23]
	v_mov_b32_e32 v2, 0
	v_cndmask_b32_e64 v1, v5, v149, s[28:29]
	v_cndmask_b32_e64 v152, v4, v148, s[28:29]
	v_cndmask_b32_e64 v145, v3, v151, s[28:29]
	v_lshl_add_u64 v[156:157], v[4:5], 0, s[16:17]
	s_mov_b32 s30, -2
	v_mov_b32_e32 v3, v2
	v_mov_b32_e32 v4, v2
	v_mov_b32_e32 v5, v2
	v_mov_b32_e32 v6, v2
	v_mov_b32_e32 v7, v2
	v_mov_b32_e32 v8, v2
	v_mov_b32_e32 v9, v2
	v_mov_b32_e32 v10, v2
	v_mov_b32_e32 v11, v2
	v_mov_b32_e32 v12, v2
	v_mov_b32_e32 v13, v2
	v_mov_b32_e32 v18, v2
	v_mov_b32_e32 v19, v2
	v_mov_b32_e32 v20, v2
	v_mov_b32_e32 v21, v2
	s_waitcnt vmcnt(0)
	v_mov_b32_e32 v26, v2
	v_mov_b32_e32 v27, v2
	v_mov_b32_e32 v28, v2
	v_mov_b32_e32 v29, v2
	v_mov_b32_e32 v34, v2
	v_mov_b32_e32 v35, v2
	v_mov_b32_e32 v36, v2
	v_mov_b32_e32 v37, v2
	v_mov_b32_e32 v42, v2
	v_mov_b32_e32 v43, v2
	v_mov_b32_e32 v44, v2
	v_mov_b32_e32 v45, v2
	v_mov_b32_e32 v50, v2
	v_mov_b32_e32 v51, v2
	v_mov_b32_e32 v52, v2
	v_mov_b32_e32 v53, v2
	v_mov_b32_e32 v14, v2
	v_mov_b32_e32 v15, v2
	v_mov_b32_e32 v16, v2
	v_mov_b32_e32 v17, v2
	v_mov_b32_e32 v22, v2
	v_mov_b32_e32 v23, v2
	v_mov_b32_e32 v24, v2
	v_mov_b32_e32 v25, v2
	v_mov_b32_e32 v30, v2
	v_mov_b32_e32 v31, v2
	v_mov_b32_e32 v32, v2
	v_mov_b32_e32 v33, v2
	v_mov_b32_e32 v38, v2
	v_mov_b32_e32 v39, v2
	v_mov_b32_e32 v40, v2
	v_mov_b32_e32 v41, v2
	v_mov_b32_e32 v46, v2
	v_mov_b32_e32 v47, v2
	v_mov_b32_e32 v48, v2
	v_mov_b32_e32 v49, v2
	v_mov_b32_e32 v54, v2
	v_mov_b32_e32 v55, v2
	v_mov_b32_e32 v56, v2
	v_mov_b32_e32 v57, v2
	v_mov_b32_e32 v58, v2
	v_mov_b32_e32 v59, v2
	v_mov_b32_e32 v60, v2
	v_mov_b32_e32 v61, v2
	v_mov_b32_e32 v62, v2
	v_mov_b32_e32 v63, v2
	v_mov_b32_e32 v64, v2
	v_mov_b32_e32 v65, v2
	v_mov_b32_e32 v66, v2
	v_mov_b32_e32 v67, v2
	v_mov_b32_e32 v68, v2
	v_mov_b32_e32 v69, v2
	v_mov_b32_e32 v70, v2
	v_mov_b32_e32 v71, v2
	v_mov_b32_e32 v72, v2
	v_mov_b32_e32 v73, v2
	v_mov_b32_e32 v74, v2
	v_mov_b32_e32 v75, v2
	v_mov_b32_e32 v76, v2
	v_mov_b32_e32 v77, v2
	v_mov_b32_e32 v82, v2
	v_mov_b32_e32 v83, v2
	v_mov_b32_e32 v84, v2
	v_mov_b32_e32 v85, v2
	v_mov_b32_e32 v90, v2
	v_mov_b32_e32 v91, v2
	v_mov_b32_e32 v92, v2
	v_mov_b32_e32 v93, v2
	v_mov_b32_e32 v98, v2
	v_mov_b32_e32 v99, v2
	v_mov_b32_e32 v100, v2
	v_mov_b32_e32 v101, v2
	v_mov_b32_e32 v106, v2
	v_mov_b32_e32 v107, v2
	v_mov_b32_e32 v108, v2
	v_mov_b32_e32 v109, v2
	v_mov_b32_e32 v114, v2
	v_mov_b32_e32 v115, v2
	v_mov_b32_e32 v116, v2
	v_mov_b32_e32 v117, v2
	v_mov_b32_e32 v78, v2
	v_mov_b32_e32 v79, v2
	v_mov_b32_e32 v80, v2
	v_mov_b32_e32 v81, v2
	v_mov_b32_e32 v86, v2
	v_mov_b32_e32 v87, v2
	v_mov_b32_e32 v88, v2
	v_mov_b32_e32 v89, v2
	v_mov_b32_e32 v94, v2
	v_mov_b32_e32 v95, v2
	v_mov_b32_e32 v96, v2
	v_mov_b32_e32 v97, v2
	v_mov_b32_e32 v102, v2
	v_mov_b32_e32 v103, v2
	v_mov_b32_e32 v104, v2
	v_mov_b32_e32 v105, v2
	v_mov_b32_e32 v110, v2
	v_mov_b32_e32 v111, v2
	v_mov_b32_e32 v112, v2
	v_mov_b32_e32 v113, v2
	v_mov_b32_e32 v118, v2
	v_mov_b32_e32 v119, v2
	v_mov_b32_e32 v120, v2
	v_mov_b32_e32 v121, v2
	v_mov_b32_e32 v122, v2
	v_mov_b32_e32 v123, v2
	v_mov_b32_e32 v124, v2
	v_mov_b32_e32 v125, v2
	v_mov_b32_e32 v126, v2
	v_mov_b32_e32 v127, v2
	v_mov_b32_e32 v128, v2
	v_mov_b32_e32 v129, v2
	s_setprio 0
	.p2align 6

.LBB0_478:
	s_cmp_lt_i32 s70, 5
	s_cselect_b64 s[2:3], -1, 0
	s_and_b64 s[38:39], s[2:3], s[0:1]
	s_andn2_b64 vcc, exec, s[38:39]
	s_cbranch_vccnz .LBB0_521
	v_and_b32_e32 v1, 7, v0
	s_cmpk_gt_i32 s94, 0xff
	v_lshrrev_b32_e32 v188, 4, v163
	v_and_b32_e32 v162, 15, v0
	v_and_b32_e32 v189, 3, v0
	v_lshrrev_b32_e32 v190, 6, v0
	s_cbranch_scc1 .LBB0_499
	s_waitcnt vmcnt(0)
	v_and_b32_e32 v9, 0xc0, v0
	v_mov_b32_e32 v164, 0
	v_lshrrev_b32_e32 v4, 2, v0
	v_and_or_b32 v192, v4, 64, v162
	v_lshlrev_b32_e32 v4, 5, v9
	v_mov_b32_e32 v5, v164
	v_and_b32_e32 v6, 48, v0
	v_lshl_add_u64 v[4:5], s[68:69], 0, v[4:5]
	v_lshlrev_b32_e32 v6, 5, v6
	v_mov_b32_e32 v7, v164
	v_lshl_add_u64 v[4:5], v[4:5], 0, v[6:7]
	s_mov_b64 s[2:3], 0x1000000
	v_lshl_add_u64 v[166:167], v[4:5], 0, s[2:3]
	v_lshlrev_b32_e32 v4, 2, v0
	v_and_b32_e32 v11, 48, v4
	v_lshlrev_b32_e32 v4, 2, v11
	v_mov_b32_e32 v5, v164
	v_lshl_add_u64 v[4:5], s[68:69], 0, v[4:5]
	v_lshlrev_b32_e32 v6, 2, v189
	v_lshrrev_b32_e32 v2, 4, v0
	v_lshl_add_u64 v[4:5], v[4:5], 0, v[6:7]
	v_lshlrev_b32_e32 v6, 2, v9
	v_and_b32_e32 v3, 24, v2
	v_lshl_add_u64 v[4:5], v[4:5], 0, v[6:7]
	s_mov_b64 s[8:9], 0x700000
	s_add_u32 s4, s68, 0x45000000
	v_or_b32_e32 v191, v3, v1
	v_lshl_add_u64 v[168:169], v[4:5], 0, s[8:9]
	v_lshlrev_b32_e32 v4, 8, v188
	s_addc_u32 s5, s69, 0
	v_or3_b32 v4, v4, v11, v9
	v_or_b32_e32 v7, 32, v191
	v_or_b32_e32 v11, 0x60, v191
	s_add_u32 s22, s68, 0x600000
	v_bfe_u32 v8, v0, 3, 4
	s_movk_i32 s6, 0xc0
	v_and_b32_e32 v6, 4, v190
	v_lshrrev_b32_e32 v9, 2, v7
	v_lshrrev_b32_e32 v12, 2, v11
	s_movk_i32 s8, 0x80
	s_addc_u32 s23, s69, 0
	v_lshlrev_b32_e32 v2, 3, v8
	v_lshl_add_u32 v10, v8, 12, 0
	v_bitop3_b32 v3, v3, v6, v1 bitop3:0x36
	v_bitop3_b32 v7, v9, v7, 12 bitop3:0x6c
	v_bitop3_b32 v9, v191, v6, 64 bitop3:0x36
	v_bitop3_b32 v11, v12, v11, 12 bitop3:0x6c
	v_bitop3_b32 v12, v191, v6, s8 bitop3:0x36
	v_bitop3_b32 v6, v191, v6, s6 bitop3:0x36
	v_lshlrev_b32_e32 v8, 11, v8
	s_add_i32 s6, 0, 0x10000
	v_lshlrev_b32_e32 v25, 11, v188
	v_add_u32_e32 v16, s6, v8
	v_add_u32_e32 v27, s6, v25
	s_add_i32 s6, 0, 0x10100
	v_add_u32_e32 v28, s6, v25
	s_add_i32 s6, 0, 0x10300
	v_add_u32_e32 v30, s6, v25
	s_add_i32 s6, 0, 0x12000
	v_add_u32_e32 v35, s6, v25
	s_add_i32 s6, 0, 0x12100
	v_add_u32_e32 v36, s6, v25
	s_add_i32 s6, 0, 0x12200
	v_add_u32_e32 v37, s6, v25
	s_add_i32 s6, 0, 0x12300
	v_add_u32_e32 v38, s6, v25
	s_add_i32 s6, 0, 0x14000
	v_add_u32_e32 v43, s6, v25
	s_add_i32 s6, 0, 0x14100
	v_and_b32_e32 v5, 12, v0
	v_add_u32_e32 v44, s6, v25
	s_add_i32 s6, 0, 0x14200
	v_or_b32_e32 v13, 0xa0, v191
	v_bitop3_b32 v20, v189, v5, 4 bitop3:0x36
	v_bitop3_b32 v5, v189, v5, 8 bitop3:0x36
	v_bitop3_b32 v23, v189, v0, 12 bitop3:0x72
	v_add_u32_e32 v45, s6, v25
	s_add_i32 s6, 0, 0x14300
	v_lshrrev_b32_e32 v14, 2, v13
	v_or_b32_e32 v19, v4, v162
	v_or_b32_e32 v21, v4, v20
	v_or_b32_e32 v22, v4, v5
	v_or_b32_e32 v24, v4, v23
	v_or_b32_e32 v31, 0x400, v4
	v_or_b32_e32 v39, 0x800, v4
	v_add_u32_e32 v46, s6, v25
	v_or_b32_e32 v4, 0xc00, v4
	s_add_i32 s6, 0, 0x16000
	v_bitop3_b32 v13, v14, v13, 12 bitop3:0x6c
	v_or_b32_e32 v14, 0xe0, v191
	v_or_b32_e32 v32, v31, v162
	v_or_b32_e32 v33, v31, v20
	v_or_b32_e32 v34, v31, v5
	v_or_b32_e32 v31, v31, v23
	v_or_b32_e32 v40, v39, v162
	v_or_b32_e32 v41, v39, v20
	v_or_b32_e32 v42, v39, v5
	v_or_b32_e32 v39, v39, v23
	v_or_b32_e32 v47, v4, v162
	v_or_b32_e32 v20, v4, v20
	v_or_b32_e32 v5, v4, v5
	v_or_b32_e32 v4, v4, v23
	v_add_u32_e32 v23, s6, v25
	s_add_i32 s6, 0, 0x16100
	v_lshrrev_b32_e32 v15, 2, v14
	s_add_i32 s9, 0, 0x10400
	v_add_u32_e32 v48, s6, v25
	s_add_i32 s6, 0, 0x16200
	v_bitop3_b32 v14, v15, v14, 12 bitop3:0x6c
	s_add_i32 s8, 0, 0x10200
	v_add_u32_e32 v18, s9, v8
	s_add_i32 s9, 0, 0x10600
	v_add_u32_e32 v49, s6, v25
	s_add_i32 s6, 0, 0x16300
	s_movk_i32 s0, 0x100
	v_lshlrev_b32_e32 v3, 4, v3
	v_lshlrev_b32_e32 v7, 4, v7
	v_lshlrev_b32_e32 v9, 4, v9
	v_lshlrev_b32_e32 v11, 4, v11
	v_lshlrev_b32_e32 v12, 4, v12
	v_lshlrev_b32_e32 v13, 4, v13
	v_lshlrev_b32_e32 v6, 4, v6
	v_lshlrev_b32_e32 v14, 4, v14
	v_lshlrev_b32_e32 v15, 4, v191
	v_add_u32_e32 v17, s8, v8
	v_add_u32_e32 v8, s9, v8
	v_lshlrev_b32_e32 v19, 4, v19
	v_lshlrev_b32_e32 v21, 4, v21
	v_lshlrev_b32_e32 v22, 4, v22
	v_lshlrev_b32_e32 v24, 4, v24
	v_lshlrev_b32_e32 v26, 4, v192
	v_add_u32_e32 v29, s8, v25
	v_lshlrev_b32_e32 v32, 4, v32
	v_lshlrev_b32_e32 v33, 4, v33
	v_lshlrev_b32_e32 v34, 4, v34
	v_lshlrev_b32_e32 v31, 4, v31
	v_lshlrev_b32_e32 v40, 4, v40
	v_lshlrev_b32_e32 v41, 4, v41
	v_lshlrev_b32_e32 v42, 4, v42
	v_lshlrev_b32_e32 v39, 4, v39
	v_lshlrev_b32_e32 v47, 4, v47
	v_lshlrev_b32_e32 v20, 4, v20
	v_lshlrev_b32_e32 v5, 4, v5
	v_lshlrev_b32_e32 v4, 4, v4
	v_add_u32_e32 v25, s6, v25
	v_lshlrev_b32_e32 v170, 1, v2
	v_mbcnt_lo_u32_b32 v2, -1, 0
	v_cmp_gt_u32_e64 s[0:1], s0, v0
	s_mov_b32 s7, 0
	v_cmp_gt_u32_e64 s[2:3], 16, v163
	s_mov_b32 s24, 0x61000000
	s_movk_i32 s25, 0x2000
	s_movk_i32 s26, 0x4000
	s_movk_i32 s27, 0x6000
	s_mov_b32 s28, 0x8000
	s_mov_b32 s29, 0xa000
	s_mov_b32 s30, 0xc000
	s_mov_b32 s31, 0xe000
	s_mov_b32 s34, 0x100000
	s_mov_b32 s35, 0x200000
	s_mov_b32 s36, 0x300000
	v_add_u32_e32 v193, v10, v3
	v_add_u32_e32 v194, v10, v7
	v_add_u32_e32 v195, v10, v9
	v_add_u32_e32 v196, v10, v11
	v_add_u32_e32 v197, v10, v12
	v_add_u32_e32 v198, v10, v13
	v_add_u32_e32 v199, v10, v6
	v_add_u32_e32 v200, v10, v14
	v_add_u32_e32 v201, v16, v15
	v_add_u32_e32 v202, v17, v15
	v_add_u32_e32 v203, v18, v15
	v_add_u32_e32 v204, v8, v15
	v_add_u32_e32 v205, 0, v19
	v_add_u32_e32 v206, 0, v21
	v_add_u32_e32 v207, 0, v22
	v_add_u32_e32 v208, 0, v24
	v_add_u32_e32 v209, v27, v26
	v_add_u32_e32 v210, v28, v26
	v_add_u32_e32 v211, v29, v26
	v_add_u32_e32 v212, v30, v26
	v_add_u32_e32 v213, 0, v32
	v_add_u32_e32 v214, 0, v33
	v_add_u32_e32 v215, 0, v34
	v_add_u32_e32 v216, 0, v31
	v_add_u32_e32 v217, v35, v26
	v_add_u32_e32 v218, v36, v26
	v_add_u32_e32 v219, v37, v26
	v_add_u32_e32 v220, v38, v26
	v_add_u32_e32 v221, 0, v40
	v_add_u32_e32 v222, 0, v41
	v_add_u32_e32 v223, 0, v42
	v_add_u32_e32 v224, 0, v39
	v_add_u32_e32 v225, v43, v26
	v_add_u32_e32 v226, v44, v26
	v_add_u32_e32 v227, v45, v26
	v_add_u32_e32 v228, v46, v26
	v_add_u32_e32 v229, 0, v47
	v_add_u32_e32 v230, 0, v20
	v_add_u32_e32 v231, 0, v5
	v_add_u32_e32 v232, 0, v4
	v_add_u32_e32 v233, v23, v26
	v_add_u32_e32 v234, v48, v26
	v_add_u32_e32 v235, v49, v26
	v_add_u32_e32 v236, v25, v26
	v_mbcnt_hi_u32_b32 v237, -1, v2
	s_mov_b32 s37, s94
	s_cmp_eq_u32 s33, 0x100
	s_cbranch_scc0 .Lscan_noremap
	s_and_b32 s98, s94, 7
	s_lshl_b32 s98, s98, 2
	s_lshr_b32 s99, s94, 3
	s_and_b32 s100, s99, 3
	s_or_b32 s98, s98, s100
	s_lshr_b32 s99, s99, 2
	s_lshl_b32 s99, s99, 5
	s_or_b32 s37, s98, s99
.Lscan_noremap:
	s_branch .LBB0_482

.LBB0_482:
	s_bfe_u32 s12, s37, 0x20005
	s_bfe_u32 s13, s37, 0x30002
	s_and_b32 s14, s37, 3
	s_cmpk_lt_u32 s37, 0x80
	s_cselect_b64 s[8:9], -1, 0
	s_and_b64 s[10:11], s[8:9], exec
	s_cselect_b32 s6, s24, 0x65000000
	s_cselect_b32 s15, 0, 31
	s_cselect_b32 s41, 1, -1
	s_add_u32 s10, s68, s6
	s_addc_u32 s11, s69, 0
	s_lshl_b32 s6, s12, 16
	s_lshl_b32 s16, s13, 8
	s_or_b32 s6, s6, s16
	s_lshl_b32 s16, s14, 7
	v_lshl_or_b32 v4, s13, 9, v191
	v_or_b32_e32 v2, s6, v191
	v_or_b32_e32 v4, s16, v4
	v_lshlrev_b32_e32 v2, 8, v2
	v_mov_b32_e32 v3, v164
	v_lshlrev_b32_e32 v4, 15, v4
	v_mov_b32_e32 v5, v164
	s_lshl_b32 s6, s12, 13
	v_lshl_add_u64 v[2:3], s[10:11], 0, v[2:3]
	v_lshl_add_u64 v[4:5], s[4:5], 0, v[4:5]
	v_mov_b32_e32 v171, v164
	s_cmp_eq_u32 s14, 0
	v_lshl_add_u64 v[4:5], v[4:5], 0, s[6:7]
	v_lshl_add_u64 v[172:173], v[2:3], 0, v[170:171]
	s_cselect_b64 s[10:11], -1, 0
	s_lshl_b32 s6, s15, 19
	v_lshl_add_u64 v[26:27], v[172:173], 0, s[6:7]
	v_add_co_u32_e32 v6, vcc, s25, v26
	v_lshl_add_u64 v[174:175], v[4:5], 0, v[170:171]
	s_nop 0
	v_addc_co_u32_e32 v7, vcc, 0, v27, vcc
	v_add_co_u32_e32 v10, vcc, s26, v26
	s_lshl_b32 s6, s15, 8
	s_nop 0
	v_addc_co_u32_e32 v11, vcc, 0, v27, vcc
	v_add_co_u32_e32 v14, vcc, s27, v26
	v_lshl_add_u64 v[42:43], v[174:175], 0, s[6:7]
	s_nop 0
	v_addc_co_u32_e32 v15, vcc, 0, v27, vcc
	v_add_co_u32_e32 v18, vcc, s28, v26
	s_ashr_i32 s6, s37, 5
	s_nop 0
	v_addc_co_u32_e32 v19, vcc, 0, v27, vcc
	v_add_co_u32_e32 v22, vcc, s29, v26
	s_and_b32 s6, s6, -4
	s_nop 0
	v_addc_co_u32_e32 v23, vcc, 0, v27, vcc
	v_add_co_u32_e32 v28, vcc, s30, v26
	s_or_b32 s14, s6, s12
	s_nop 0
	v_addc_co_u32_e32 v29, vcc, 0, v27, vcc
	v_add_co_u32_e32 v30, vcc, s31, v26
	s_lshl_b32 s6, s14, 8
	s_nop 0
	v_addc_co_u32_e32 v31, vcc, 0, v27, vcc
	s_lshl_b32 s17, s13, 5
	v_add_co_u32_e32 v38, vcc, s34, v42
	s_or_b32 s12, s6, s17
	s_nop 0
	v_addc_co_u32_e32 v39, vcc, 0, v43, vcc
	s_ashr_i32 s13, s12, 31
	v_add_co_u32_e32 v44, vcc, s35, v42
	s_and_b64 s[10:11], s[10:11], s[0:1]
	s_lshl_b64 s[12:13], s[12:13], 2
	v_addc_co_u32_e32 v45, vcc, 0, v43, vcc
	s_add_u32 s12, s22, s12
	v_add_co_u32_e32 v46, vcc, s36, v42
	s_addc_u32 s13, s23, s13
	s_lshl_b32 s6, s15, 2
	v_addc_co_u32_e32 v47, vcc, 0, v43, vcc
	v_mov_b32_e32 v50, s6
	global_load_dwordx4 v[2:5], v[26:27], off
	s_nop 0
	global_load_dwordx4 v[6:9], v[6:7], off
	s_nop 0
	global_load_dwordx4 v[10:13], v[10:11], off
	s_nop 0
	global_load_dwordx4 v[14:17], v[14:15], off
	s_nop 0
	global_load_dwordx4 v[18:21], v[18:19], off
	s_nop 0
	global_load_dwordx4 v[22:25], v[22:23], off
	s_nop 0
	global_load_dwordx4 v[26:29], v[28:29], off
	s_nop 0
	global_load_dwordx4 v[30:33], v[30:31], off
	s_nop 0
	global_load_dwordx4 v[34:37], v[42:43], off
	s_nop 0
	global_load_dwordx4 v[38:41], v[38:39], off
	s_nop 0
	global_load_dwordx4 v[42:45], v[44:45], off
	s_nop 0
	global_load_dwordx4 v[46:49], v[46:47], off
	s_ashr_i32 s15, s14, 31
	global_load_dword v182, v50, s[12:13]
	v_and_b32_e32 v50, 64, v192
	v_or_b32_e32 v50, s16, v50
	s_lshl_b64 s[14:15], s[14:15], 8
	v_lshlrev_b32_e32 v50, 9, v50
	v_and_b32_e32 v51, 15, v192
	v_lshl_or_b32 v50, v51, 4, v50
	v_mov_b32_e32 v51, v164
	v_mov_b32_e32 v165, v164
	s_mov_b32 s40, 31
	s_or_b32 s14, s14, s17
	s_and_b64 s[16:17], s[10:11], s[2:3]
	v_lshl_add_u64 v[176:177], v[166:167], 0, v[50:51]
	s_mov_b32 s6, 0
	v_mov_b64_e32 v[178:179], v[164:165]
	v_mov_b64_e32 v[180:181], v[164:165]
	v_mov_b32_e32 v50, v164
	v_mov_b32_e32 v52, v164
	v_mov_b32_e32 v53, v164
	v_mov_b32_e32 v54, v164
	v_mov_b32_e32 v55, v164
	v_mov_b32_e32 v56, v164
	v_mov_b32_e32 v57, v164
	v_mov_b32_e32 v58, v164
	v_mov_b32_e32 v59, v164
	v_mov_b32_e32 v60, v164
	v_mov_b32_e32 v61, v164
	v_mov_b32_e32 v62, v164
	v_mov_b32_e32 v63, v164
	v_mov_b32_e32 v64, v164
	v_mov_b32_e32 v65, v164
	v_mov_b32_e32 v66, v164
	v_mov_b32_e32 v67, v164
	v_mov_b32_e32 v68, v164
	v_mov_b32_e32 v69, v164
	v_mov_b32_e32 v70, v164
	v_mov_b32_e32 v71, v164
	v_mov_b32_e32 v72, v164
	v_mov_b32_e32 v73, v164
	v_mov_b32_e32 v74, v164
	v_mov_b32_e32 v75, v164
	v_mov_b32_e32 v76, v164
	v_mov_b32_e32 v77, v164
	v_mov_b32_e32 v78, v164
	v_mov_b32_e32 v79, v164
	v_mov_b32_e32 v80, v164
	v_mov_b32_e32 v81, v164
	v_mov_b32_e32 v82, v164
	v_mov_b32_e32 v83, v164
	v_mov_b32_e32 v84, v164
	v_mov_b32_e32 v85, v164
	v_mov_b32_e32 v86, v164
	v_mov_b32_e32 v87, v164
	v_mov_b32_e32 v88, v164
	v_mov_b32_e32 v89, v164
	v_mov_b32_e32 v90, v164
	v_mov_b32_e32 v91, v164
	v_mov_b32_e32 v92, v164
	v_mov_b32_e32 v93, v164
	v_mov_b32_e32 v94, v164
	v_mov_b32_e32 v95, v164
	v_mov_b32_e32 v96, v164
	v_mov_b32_e32 v97, v164
	v_mov_b32_e32 v98, v164
	v_mov_b32_e32 v99, v164
	v_mov_b32_e32 v100, v164
	v_mov_b32_e32 v101, v164
	v_mov_b32_e32 v102, v164
	v_mov_b32_e32 v103, v164
	v_mov_b32_e32 v104, v164
	v_mov_b32_e32 v105, v164
	v_mov_b32_e32 v106, v164
	v_mov_b32_e32 v107, v164
	v_mov_b32_e32 v108, v164
	v_mov_b32_e32 v109, v164
	v_mov_b32_e32 v110, v164
	v_mov_b32_e32 v111, v164
	v_mov_b32_e32 v112, v164
	v_mov_b32_e32 v113, v164
	s_waitcnt vmcnt(0)
	s_barrier
	s_branch .LBB0_484

.LBB0_487:
	s_andn2_b64 vcc, exec, s[20:21]
	s_waitcnt vmcnt(20)
	ds_write_b128 v193, v[2:5]
	s_waitcnt vmcnt(19)
	ds_write_b128 v194, v[6:9]
	s_waitcnt vmcnt(18)
	ds_write_b128 v195, v[10:13]
	s_waitcnt vmcnt(17)
	ds_write_b128 v196, v[14:17]
	s_waitcnt vmcnt(16)
	ds_write_b128 v197, v[18:21]
	s_waitcnt vmcnt(15)
	ds_write_b128 v198, v[22:25]
	s_waitcnt vmcnt(14)
	ds_write_b128 v199, v[26:29]
	s_waitcnt vmcnt(13)
	ds_write_b128 v200, v[30:33]
	s_waitcnt vmcnt(12)
	ds_write_b128 v201, v[34:37]
	s_waitcnt vmcnt(11)
	ds_write_b128 v202, v[38:41]
	s_waitcnt vmcnt(10)
	ds_write_b128 v203, v[42:45]
	s_waitcnt vmcnt(9)
	ds_write_b128 v204, v[46:49]
	s_waitcnt lgkmcnt(0)
	s_barrier
	s_cbranch_vccnz .LBB0_489
	s_ashr_i32 s19, s18, 31
	s_lshl_b64 s[20:21], s[18:19], 19
	v_lshl_add_u64 v[26:27], v[172:173], 0, s[20:21]
	v_add_co_u32_e32 v6, vcc, 0x2000, v26
	s_lshl_b32 s18, s18, 7
	s_nop 0
	v_addc_co_u32_e32 v7, vcc, 0, v27, vcc
	v_add_co_u32_e32 v10, vcc, 0x4000, v26
	s_ashr_i32 s19, s18, 31
	s_nop 0
	v_addc_co_u32_e32 v11, vcc, 0, v27, vcc
	v_add_co_u32_e32 v14, vcc, 0x6000, v26
	v_lshl_add_u64 v[42:43], s[18:19], 1, v[174:175]
	s_nop 0
	v_addc_co_u32_e32 v15, vcc, 0, v27, vcc
	v_add_co_u32_e32 v18, vcc, 0x8000, v26
	global_load_dwordx4 v[2:5], v[26:27], off
	s_nop 0
	global_load_dwordx4 v[6:9], v[6:7], off
	v_addc_co_u32_e32 v19, vcc, 0, v27, vcc
	v_add_co_u32_e32 v22, vcc, 0xa000, v26
	global_load_dwordx4 v[10:13], v[10:11], off
	s_nop 0
	global_load_dwordx4 v[14:17], v[14:15], off
	v_addc_co_u32_e32 v23, vcc, 0, v27, vcc
	v_add_co_u32_e32 v28, vcc, 0xc000, v26
	global_load_dwordx4 v[18:21], v[18:19], off
	s_nop 0
	global_load_dwordx4 v[22:25], v[22:23], off
	v_addc_co_u32_e32 v29, vcc, 0, v27, vcc
	v_add_co_u32_e32 v30, vcc, 0xe000, v26
	s_nop 1
	v_addc_co_u32_e32 v31, vcc, 0, v27, vcc
	v_add_co_u32_e32 v38, vcc, 0x100000, v42
	global_load_dwordx4 v[26:29], v[28:29], off
	s_nop 0
	global_load_dwordx4 v[30:33], v[30:31], off
	v_addc_co_u32_e32 v39, vcc, 0, v43, vcc
	v_add_co_u32_e32 v44, vcc, 0x200000, v42
	global_load_dwordx4 v[34:37], v[42:43], off
	s_nop 0
	global_load_dwordx4 v[38:41], v[38:39], off
	v_addc_co_u32_e32 v45, vcc, 0, v43, vcc
	v_add_co_u32_e32 v46, vcc, 0x300000, v42
	s_nop 1
	v_addc_co_u32_e32 v47, vcc, 0, v43, vcc
	global_load_dwordx4 v[42:45], v[44:45], off
	s_nop 0
	global_load_dwordx4 v[46:49], v[46:47], off

.LBB0_491:
	s_or_b64 exec, exec, s[20:21]
	ds_read_b128 v[122:125], v205
	ds_read_b128 v[130:133], v209
	ds_read_b128 v[126:129], v206
	ds_read_b128 v[134:137], v210
	ds_read_b128 v[114:117], v207
	ds_read_b128 v[118:121], v208
	ds_read_b128 v[138:141], v211
	ds_read_b128 v[142:145], v212
	s_waitcnt vmcnt(20)
	v_pk_mul_f32 v[112:113], v[112:113], v[182:183] op_sel_hi:[1,0]
	v_pk_mul_f32 v[110:111], v[110:111], v[182:183] op_sel_hi:[1,0]
	v_pk_mul_f32 v[108:109], v[108:109], v[182:183] op_sel_hi:[1,0]
	v_pk_mul_f32 v[106:107], v[106:107], v[182:183] op_sel_hi:[1,0]
	v_pk_mul_f32 v[96:97], v[96:97], v[182:183] op_sel_hi:[1,0]
	v_pk_mul_f32 v[94:95], v[94:95], v[182:183] op_sel_hi:[1,0]
	v_pk_mul_f32 v[92:93], v[92:93], v[182:183] op_sel_hi:[1,0]
	v_pk_mul_f32 v[90:91], v[90:91], v[182:183] op_sel_hi:[1,0]
	v_pk_mul_f32 v[80:81], v[80:81], v[182:183] op_sel_hi:[1,0]
	v_pk_mul_f32 v[78:79], v[78:79], v[182:183] op_sel_hi:[1,0]
	v_pk_mul_f32 v[76:77], v[76:77], v[182:183] op_sel_hi:[1,0]
	v_pk_mul_f32 v[74:75], v[74:75], v[182:183] op_sel_hi:[1,0]
	v_pk_mul_f32 v[64:65], v[64:65], v[182:183] op_sel_hi:[1,0]
	v_pk_mul_f32 v[62:63], v[62:63], v[182:183] op_sel_hi:[1,0]
	v_pk_mul_f32 v[60:61], v[60:61], v[182:183] op_sel_hi:[1,0]
	v_pk_mul_f32 v[58:59], v[58:59], v[182:183] op_sel_hi:[1,0]
	s_waitcnt lgkmcnt(6)
	v_mfma_f32_16x16x32_bf16 v[110:113], v[122:125], v[130:133], v[110:113]
	v_mul_f32_e64 v104, v104, v182
	v_mul_f32_e64 v105, v105, v182
	v_pk_mul_f32 v[102:103], v[102:103], v[182:183] op_sel_hi:[1,0]
	v_pk_mul_f32 v[100:101], v[100:101], v[182:183] op_sel_hi:[1,0]
	s_waitcnt lgkmcnt(4)
	v_mfma_f32_16x16x32_bf16 v[106:109], v[122:125], v[134:137], v[106:109]
	v_mul_f32_e64 v98, v98, v182
	v_mul_f32_e64 v99, v99, v182
	v_pk_mul_f32 v[88:89], v[88:89], v[182:183] op_sel_hi:[1,0]
	v_pk_mul_f32 v[86:87], v[86:87], v[182:183] op_sel_hi:[1,0]
	v_mfma_f32_16x16x32_bf16 v[94:97], v[126:129], v[130:133], v[94:97]
	v_mul_f32_e64 v84, v84, v182
	v_mul_f32_e64 v85, v85, v182
	v_pk_mul_f32 v[82:83], v[82:83], v[182:183] op_sel_hi:[1,0]
	v_pk_mul_f32 v[72:73], v[72:73], v[182:183] op_sel_hi:[1,0]
	v_mfma_f32_16x16x32_bf16 v[90:93], v[126:129], v[134:137], v[90:93]
	v_mul_f32_e64 v70, v70, v182
	v_mul_f32_e64 v71, v71, v182
	v_pk_mul_f32 v[68:69], v[68:69], v[182:183] op_sel_hi:[1,0]
	v_pk_mul_f32 v[66:67], v[66:67], v[182:183] op_sel_hi:[1,0]
	s_waitcnt lgkmcnt(3)
	v_mfma_f32_16x16x32_bf16 v[78:81], v[114:117], v[130:133], v[78:81]
	v_mov_b32_e32 v165, v164
	v_mov_b64_e32 v[186:187], v[164:165]
	v_mov_b64_e32 v[184:185], v[164:165]
	v_mfma_f32_16x16x32_bf16 v[74:77], v[114:117], v[134:137], v[74:77]
	s_waitcnt lgkmcnt(2)
	v_mfma_f32_16x16x32_bf16 v[62:65], v[118:121], v[130:133], v[62:65]
	v_mul_f32_e64 v132, v56, v182
	v_mul_f32_e64 v133, v57, v182
	v_pk_mul_f32 v[130:131], v[54:55], v[182:183] op_sel_hi:[1,0]
	v_mfma_f32_16x16x32_bf16 v[56:59], v[118:121], v[134:137], v[58:61]
	v_mul_f32_e64 v136, v52, v182
	v_mul_f32_e64 v137, v53, v182
	v_pk_mul_f32 v[134:135], v[50:51], v[182:183] op_sel_hi:[1,0]
	s_waitcnt lgkmcnt(1)
	v_mfma_f32_16x16x32_bf16 v[102:105], v[122:125], v[138:141], v[102:105]
	s_waitcnt lgkmcnt(0)
	v_mfma_f32_16x16x32_bf16 v[98:101], v[122:125], v[142:145], v[98:101]
	v_mfma_f32_16x16x32_bf16 v[86:89], v[126:129], v[138:141], v[86:89]
	v_mfma_f32_16x16x32_bf16 v[82:85], v[126:129], v[142:145], v[82:85]
	v_mfma_f32_16x16x32_bf16 v[70:73], v[114:117], v[138:141], v[70:73]
	v_mfma_f32_16x16x32_bf16 v[66:69], v[114:117], v[142:145], v[66:69]
	v_mfma_f32_16x16x32_bf16 v[50:53], v[118:121], v[138:141], v[130:133]
	v_mfma_f32_16x16x32_bf16 v[138:141], v[118:121], v[142:145], v[134:137]
	s_and_saveexec_b64 s[18:19], s[10:11]
	s_cbranch_execz .LBB0_493
	v_lshlrev_b32_e32 v55, 16, v126
	v_lshlrev_b32_e32 v54, 16, v122
	v_and_b32_e32 v61, 0xffff0000, v126
	v_and_b32_e32 v60, 0xffff0000, v122
	v_pk_add_f32 v[54:55], v[54:55], v[60:61]
	v_lshlrev_b32_e32 v61, 16, v127
	v_lshlrev_b32_e32 v60, 16, v123
	v_and_b32_e32 v127, 0xffff0000, v127
	v_and_b32_e32 v126, 0xffff0000, v123
	v_pk_add_f32 v[60:61], v[60:61], v[126:127]
	v_and_b32_e32 v123, 0xffff0000, v128
	v_pk_add_f32 v[54:55], v[54:55], v[60:61]
	v_lshlrev_b32_e32 v61, 16, v128
	v_lshlrev_b32_e32 v60, 16, v124
	v_and_b32_e32 v122, 0xffff0000, v124
	v_pk_add_f32 v[60:61], v[60:61], v[122:123]
	v_lshlrev_b32_e32 v123, 16, v129
	v_lshlrev_b32_e32 v122, 16, v125
	v_and_b32_e32 v127, 0xffff0000, v129
	v_and_b32_e32 v126, 0xffff0000, v125
	v_pk_add_f32 v[122:123], v[122:123], v[126:127]
	s_nop 0
	v_pk_add_f32 v[60:61], v[60:61], v[122:123]
	s_nop 0
	v_pk_add_f32 v[54:55], v[54:55], v[60:61]
	v_and_b32_e32 v61, 0xffff0000, v118
	v_pk_add_f32 v[186:187], v[54:55], 0 op_sel_hi:[1,0]
	v_lshlrev_b32_e32 v55, 16, v118
	v_lshlrev_b32_e32 v54, 16, v114
	v_and_b32_e32 v60, 0xffff0000, v114
	v_pk_add_f32 v[54:55], v[54:55], v[60:61]
	v_lshlrev_b32_e32 v61, 16, v119
	v_lshlrev_b32_e32 v60, 16, v115
	v_and_b32_e32 v119, 0xffff0000, v119
	v_and_b32_e32 v118, 0xffff0000, v115
	v_pk_add_f32 v[60:61], v[60:61], v[118:119]
	v_and_b32_e32 v115, 0xffff0000, v120
	v_pk_add_f32 v[54:55], v[54:55], v[60:61]
	v_lshlrev_b32_e32 v61, 16, v120
	v_lshlrev_b32_e32 v60, 16, v116
	v_and_b32_e32 v114, 0xffff0000, v116
	v_pk_add_f32 v[60:61], v[60:61], v[114:115]
	v_lshlrev_b32_e32 v115, 16, v121
	v_lshlrev_b32_e32 v114, 16, v117
	v_and_b32_e32 v119, 0xffff0000, v121
	v_and_b32_e32 v118, 0xffff0000, v117
	v_pk_add_f32 v[114:115], v[114:115], v[118:119]
	s_nop 0
	v_pk_add_f32 v[60:61], v[60:61], v[114:115]
	s_nop 0
	v_pk_add_f32 v[54:55], v[54:55], v[60:61]
	s_nop 0
	v_pk_add_f32 v[184:185], v[54:55], 0 op_sel_hi:[1,0]

.LBB0_762:
	s_ashr_i32 s19, s18, 31
	s_lshl_b64 s[20:21], s[18:19], 22
	s_add_u32 s20, s34, s20
	s_addc_u32 s21, s35, s21
	s_and_b64 s[22:23], s[0:1], exec
	s_cselect_b32 s19, s21, s27
	s_cselect_b32 s53, s20, s26
	s_ashr_i32 s17, s16, 31
	s_lshl_b64 s[22:23], s[16:17], 22
	s_add_u32 s22, s36, s22
	s_addc_u32 s23, s37, s23
	s_and_b64 s[30:31], s[0:1], exec
	s_cselect_b32 s17, s23, s29
	s_cselect_b32 s56, s22, s28
	s_add_u32 s26, s26, 0x200080
	s_addc_u32 s27, s27, 0
	s_add_u32 s57, s28, 0x100
	v_mov_b32_e32 v2, 0
	s_addc_u32 s58, s29, 0
	s_mov_b32 s59, -2
	v_mov_b32_e32 v3, v2
	v_mov_b32_e32 v4, v2
	v_mov_b32_e32 v5, v2
	v_mov_b32_e32 v6, v2
	v_mov_b32_e32 v7, v2
	v_mov_b32_e32 v8, v2
	v_mov_b32_e32 v9, v2
	v_mov_b32_e32 v14, v2
	v_mov_b32_e32 v15, v2
	v_mov_b32_e32 v16, v2
	v_mov_b32_e32 v17, v2
	v_mov_b32_e32 v22, v2
	v_mov_b32_e32 v23, v2
	v_mov_b32_e32 v24, v2
	v_mov_b32_e32 v25, v2
	v_mov_b32_e32 v30, v2
	v_mov_b32_e32 v31, v2
	v_mov_b32_e32 v32, v2
	v_mov_b32_e32 v33, v2
	v_mov_b32_e32 v38, v2
	v_mov_b32_e32 v39, v2
	v_mov_b32_e32 v40, v2
	v_mov_b32_e32 v41, v2
	v_mov_b32_e32 v46, v2
	v_mov_b32_e32 v47, v2
	v_mov_b32_e32 v48, v2
	v_mov_b32_e32 v49, v2
	v_mov_b32_e32 v54, v2
	v_mov_b32_e32 v55, v2
	v_mov_b32_e32 v56, v2
	v_mov_b32_e32 v57, v2
	v_mov_b32_e32 v10, v2
	v_mov_b32_e32 v11, v2
	v_mov_b32_e32 v12, v2
	v_mov_b32_e32 v13, v2
	v_mov_b32_e32 v18, v2
	v_mov_b32_e32 v19, v2
	v_mov_b32_e32 v20, v2
	v_mov_b32_e32 v21, v2
	v_mov_b32_e32 v26, v2
	v_mov_b32_e32 v27, v2
	v_mov_b32_e32 v28, v2
	v_mov_b32_e32 v29, v2
	v_mov_b32_e32 v34, v2
	v_mov_b32_e32 v35, v2
	v_mov_b32_e32 v36, v2
	v_mov_b32_e32 v37, v2
	v_mov_b32_e32 v42, v2
	v_mov_b32_e32 v43, v2
	v_mov_b32_e32 v44, v2
	v_mov_b32_e32 v45, v2
	v_mov_b32_e32 v50, v2
	v_mov_b32_e32 v51, v2
	v_mov_b32_e32 v52, v2
	v_mov_b32_e32 v53, v2
	v_mov_b32_e32 v58, v2
	v_mov_b32_e32 v59, v2
	v_mov_b32_e32 v60, v2
	v_mov_b32_e32 v61, v2
	v_mov_b32_e32 v62, v2
	v_mov_b32_e32 v63, v2
	v_mov_b32_e32 v64, v2
	v_mov_b32_e32 v65, v2
	v_mov_b32_e32 v66, v2
	v_mov_b32_e32 v67, v2
	v_mov_b32_e32 v68, v2
	v_mov_b32_e32 v69, v2
	v_mov_b32_e32 v70, v2
	v_mov_b32_e32 v71, v2
	v_mov_b32_e32 v72, v2
	v_mov_b32_e32 v73, v2
	v_mov_b32_e32 v78, v2
	v_mov_b32_e32 v79, v2
	v_mov_b32_e32 v80, v2
	v_mov_b32_e32 v81, v2
	v_mov_b32_e32 v86, v2
	v_mov_b32_e32 v87, v2
	v_mov_b32_e32 v88, v2
	v_mov_b32_e32 v89, v2
	v_mov_b32_e32 v94, v2
	v_mov_b32_e32 v95, v2
	v_mov_b32_e32 v96, v2
	v_mov_b32_e32 v97, v2
	v_mov_b32_e32 v102, v2
	v_mov_b32_e32 v103, v2
	v_mov_b32_e32 v104, v2
	v_mov_b32_e32 v105, v2
	v_mov_b32_e32 v110, v2
	v_mov_b32_e32 v111, v2
	v_mov_b32_e32 v112, v2
	v_mov_b32_e32 v113, v2
	v_mov_b32_e32 v118, v2
	v_mov_b32_e32 v119, v2
	v_mov_b32_e32 v120, v2
	v_mov_b32_e32 v121, v2
	v_mov_b32_e32 v74, v2
	v_mov_b32_e32 v75, v2
	v_mov_b32_e32 v76, v2
	v_mov_b32_e32 v77, v2
	v_mov_b32_e32 v82, v2
	v_mov_b32_e32 v83, v2
	v_mov_b32_e32 v84, v2
	v_mov_b32_e32 v85, v2
	v_mov_b32_e32 v90, v2
	v_mov_b32_e32 v91, v2
	v_mov_b32_e32 v92, v2
	v_mov_b32_e32 v93, v2
	v_mov_b32_e32 v98, v2
	v_mov_b32_e32 v99, v2
	v_mov_b32_e32 v100, v2
	v_mov_b32_e32 v101, v2
	v_mov_b32_e32 v106, v2
	v_mov_b32_e32 v107, v2
	v_mov_b32_e32 v108, v2
	v_mov_b32_e32 v109, v2
	v_mov_b32_e32 v114, v2
	v_mov_b32_e32 v115, v2
	v_mov_b32_e32 v116, v2
	v_mov_b32_e32 v117, v2
	v_mov_b32_e32 v122, v2
	v_mov_b32_e32 v123, v2
	v_mov_b32_e32 v124, v2
	v_mov_b32_e32 v125, v2
	v_mov_b32_e32 v126, v2
	v_mov_b32_e32 v127, v2
	v_mov_b32_e32 v128, v2
	v_mov_b32_e32 v129, v2
	s_setprio 0
	.p2align 6

.LBB0_915:
	s_ashr_i32 s19, s18, 31
	s_lshl_b64 s[20:21], s[18:19], 21
	s_add_u32 s20, s54, s20
	s_addc_u32 s21, s55, s21
	s_and_b64 s[22:23], s[0:1], exec
	s_cselect_b32 s19, s21, s27
	s_cselect_b32 s53, s20, s26
	s_ashr_i32 s17, s16, 31
	s_lshl_b64 s[22:23], s[16:17], 21
	s_add_u32 s22, s36, s22
	s_addc_u32 s23, s37, s23
	s_and_b64 s[30:31], s[0:1], exec
	s_cselect_b32 s17, s23, s29
	s_cselect_b32 s56, s22, s28
	s_add_u32 s26, s26, 0x100080
	s_addc_u32 s27, s27, 0
	s_add_u32 s57, s28, 0x100
	v_mov_b32_e32 v2, 0
	s_addc_u32 s58, s29, 0
	s_mov_b32 s59, -2
	v_mov_b32_e32 v3, v2
	v_mov_b32_e32 v4, v2
	v_mov_b32_e32 v5, v2
	v_mov_b32_e32 v6, v2
	v_mov_b32_e32 v7, v2
	v_mov_b32_e32 v8, v2
	v_mov_b32_e32 v9, v2
	v_mov_b32_e32 v18, v2
	v_mov_b32_e32 v19, v2
	v_mov_b32_e32 v20, v2
	v_mov_b32_e32 v21, v2
	v_mov_b32_e32 v22, v2
	v_mov_b32_e32 v23, v2
	v_mov_b32_e32 v24, v2
	v_mov_b32_e32 v25, v2
	v_mov_b32_e32 v34, v2
	v_mov_b32_e32 v35, v2
	v_mov_b32_e32 v36, v2
	v_mov_b32_e32 v37, v2
	v_mov_b32_e32 v38, v2
	v_mov_b32_e32 v39, v2
	v_mov_b32_e32 v40, v2
	v_mov_b32_e32 v41, v2
	v_mov_b32_e32 v50, v2
	v_mov_b32_e32 v51, v2
	v_mov_b32_e32 v52, v2
	v_mov_b32_e32 v53, v2
	v_mov_b32_e32 v54, v2
	v_mov_b32_e32 v55, v2
	v_mov_b32_e32 v56, v2
	v_mov_b32_e32 v57, v2
	v_mov_b32_e32 v10, v2
	v_mov_b32_e32 v11, v2
	v_mov_b32_e32 v12, v2
	v_mov_b32_e32 v13, v2
	v_mov_b32_e32 v14, v2
	v_mov_b32_e32 v15, v2
	v_mov_b32_e32 v16, v2
	v_mov_b32_e32 v17, v2
	v_mov_b32_e32 v26, v2
	v_mov_b32_e32 v27, v2
	v_mov_b32_e32 v28, v2
	v_mov_b32_e32 v29, v2
	v_mov_b32_e32 v30, v2
	v_mov_b32_e32 v31, v2
	v_mov_b32_e32 v32, v2
	v_mov_b32_e32 v33, v2
	v_mov_b32_e32 v42, v2
	v_mov_b32_e32 v43, v2
	v_mov_b32_e32 v44, v2
	v_mov_b32_e32 v45, v2
	v_mov_b32_e32 v46, v2
	v_mov_b32_e32 v47, v2
	v_mov_b32_e32 v48, v2
	v_mov_b32_e32 v49, v2
	v_mov_b32_e32 v58, v2
	v_mov_b32_e32 v59, v2
	v_mov_b32_e32 v60, v2
	v_mov_b32_e32 v61, v2
	v_mov_b32_e32 v62, v2
	v_mov_b32_e32 v63, v2
	v_mov_b32_e32 v64, v2
	v_mov_b32_e32 v65, v2
	v_mov_b32_e32 v66, v2
	v_mov_b32_e32 v67, v2
	v_mov_b32_e32 v68, v2
	v_mov_b32_e32 v69, v2
	v_mov_b32_e32 v70, v2
	v_mov_b32_e32 v71, v2
	v_mov_b32_e32 v72, v2
	v_mov_b32_e32 v73, v2
	v_mov_b32_e32 v82, v2
	v_mov_b32_e32 v83, v2
	v_mov_b32_e32 v84, v2
	v_mov_b32_e32 v85, v2
	v_mov_b32_e32 v86, v2
	v_mov_b32_e32 v87, v2
	v_mov_b32_e32 v88, v2
	v_mov_b32_e32 v89, v2
	v_mov_b32_e32 v98, v2
	v_mov_b32_e32 v99, v2
	v_mov_b32_e32 v100, v2
	v_mov_b32_e32 v101, v2
	v_mov_b32_e32 v102, v2
	v_mov_b32_e32 v103, v2
	v_mov_b32_e32 v104, v2
	v_mov_b32_e32 v105, v2
	v_mov_b32_e32 v114, v2
	v_mov_b32_e32 v115, v2
	v_mov_b32_e32 v116, v2
	v_mov_b32_e32 v117, v2
	v_mov_b32_e32 v118, v2
	v_mov_b32_e32 v119, v2
	v_mov_b32_e32 v120, v2
	v_mov_b32_e32 v121, v2
	v_mov_b32_e32 v74, v2
	v_mov_b32_e32 v75, v2
	v_mov_b32_e32 v76, v2
	v_mov_b32_e32 v77, v2
	v_mov_b32_e32 v78, v2
	v_mov_b32_e32 v79, v2
	v_mov_b32_e32 v80, v2
	v_mov_b32_e32 v81, v2
	v_mov_b32_e32 v90, v2
	v_mov_b32_e32 v91, v2
	v_mov_b32_e32 v92, v2
	v_mov_b32_e32 v93, v2
	v_mov_b32_e32 v94, v2
	v_mov_b32_e32 v95, v2
	v_mov_b32_e32 v96, v2
	v_mov_b32_e32 v97, v2
	v_mov_b32_e32 v106, v2
	v_mov_b32_e32 v107, v2
	v_mov_b32_e32 v108, v2
	v_mov_b32_e32 v109, v2
	v_mov_b32_e32 v110, v2
	v_mov_b32_e32 v111, v2
	v_mov_b32_e32 v112, v2
	v_mov_b32_e32 v113, v2
	v_mov_b32_e32 v122, v2
	v_mov_b32_e32 v123, v2
	v_mov_b32_e32 v124, v2
	v_mov_b32_e32 v125, v2
	v_mov_b32_e32 v126, v2
	v_mov_b32_e32 v127, v2
	v_mov_b32_e32 v128, v2
	v_mov_b32_e32 v129, v2
	s_setprio 0
	.p2align 6

.LBB0_947:
	s_or_b64 exec, exec, s[48:49]
	v_ashrrev_i32_e32 v147, 31, v146
	v_lshlrev_b64 v[6:7], 21, v[146:147]
	v_ashrrev_i32_e32 v145, 31, v144
	v_lshl_add_u64 v[148:149], s[6:7], 0, v[6:7]
	v_lshlrev_b64 v[6:7], 21, v[144:145]
	v_lshl_add_u64 v[150:151], s[54:55], 0, v[6:7]
	v_cndmask_b32_e64 v154, v2, v150, s[44:45]
	v_lshl_add_u64 v[158:159], v[2:3], 0, s[30:31]
	v_mov_b32_e32 v2, 0
	v_cndmask_b32_e64 v1, v5, v149, s[44:45]
	v_cndmask_b32_e64 v152, v4, v148, s[44:45]
	v_cndmask_b32_e64 v145, v3, v151, s[44:45]
	v_lshl_add_u64 v[156:157], v[4:5], 0, s[22:23]
	s_mov_b32 s46, -2
	v_mov_b32_e32 v3, v2
	v_mov_b32_e32 v4, v2
	v_mov_b32_e32 v5, v2
	v_mov_b32_e32 v6, v2
	v_mov_b32_e32 v7, v2
	v_mov_b32_e32 v8, v2
	v_mov_b32_e32 v9, v2
	v_mov_b32_e32 v18, v2
	v_mov_b32_e32 v19, v2
	v_mov_b32_e32 v20, v2
	v_mov_b32_e32 v21, v2
	v_mov_b32_e32 v22, v2
	v_mov_b32_e32 v23, v2
	v_mov_b32_e32 v24, v2
	v_mov_b32_e32 v25, v2
	v_mov_b32_e32 v34, v2
	v_mov_b32_e32 v35, v2
	v_mov_b32_e32 v36, v2
	v_mov_b32_e32 v37, v2
	v_mov_b32_e32 v38, v2
	v_mov_b32_e32 v39, v2
	v_mov_b32_e32 v40, v2
	v_mov_b32_e32 v41, v2
	v_mov_b32_e32 v50, v2
	v_mov_b32_e32 v51, v2
	v_mov_b32_e32 v52, v2
	v_mov_b32_e32 v53, v2
	v_mov_b32_e32 v54, v2
	v_mov_b32_e32 v55, v2
	v_mov_b32_e32 v56, v2
	v_mov_b32_e32 v57, v2
	v_mov_b32_e32 v10, v2
	v_mov_b32_e32 v11, v2
	v_mov_b32_e32 v12, v2
	v_mov_b32_e32 v13, v2
	v_mov_b32_e32 v14, v2
	v_mov_b32_e32 v15, v2
	v_mov_b32_e32 v16, v2
	v_mov_b32_e32 v17, v2
	v_mov_b32_e32 v26, v2
	v_mov_b32_e32 v27, v2
	v_mov_b32_e32 v28, v2
	v_mov_b32_e32 v29, v2
	v_mov_b32_e32 v30, v2
	v_mov_b32_e32 v31, v2
	v_mov_b32_e32 v32, v2
	v_mov_b32_e32 v33, v2
	v_mov_b32_e32 v42, v2
	v_mov_b32_e32 v43, v2
	v_mov_b32_e32 v44, v2
	v_mov_b32_e32 v45, v2
	v_mov_b32_e32 v46, v2
	v_mov_b32_e32 v47, v2
	v_mov_b32_e32 v48, v2
	v_mov_b32_e32 v49, v2
	v_mov_b32_e32 v58, v2
	v_mov_b32_e32 v59, v2
	v_mov_b32_e32 v60, v2
	v_mov_b32_e32 v61, v2
	v_mov_b32_e32 v62, v2
	v_mov_b32_e32 v63, v2
	v_mov_b32_e32 v64, v2
	v_mov_b32_e32 v65, v2
	v_mov_b32_e32 v66, v2
	v_mov_b32_e32 v67, v2
	v_mov_b32_e32 v68, v2
	v_mov_b32_e32 v69, v2
	v_mov_b32_e32 v70, v2
	v_mov_b32_e32 v71, v2
	v_mov_b32_e32 v72, v2
	v_mov_b32_e32 v73, v2
	v_mov_b32_e32 v82, v2
	v_mov_b32_e32 v83, v2
	v_mov_b32_e32 v84, v2
	v_mov_b32_e32 v85, v2
	v_mov_b32_e32 v86, v2
	v_mov_b32_e32 v87, v2
	v_mov_b32_e32 v88, v2
	v_mov_b32_e32 v89, v2
	v_mov_b32_e32 v98, v2
	v_mov_b32_e32 v99, v2
	v_mov_b32_e32 v100, v2
	v_mov_b32_e32 v101, v2
	v_mov_b32_e32 v102, v2
	v_mov_b32_e32 v103, v2
	v_mov_b32_e32 v104, v2
	v_mov_b32_e32 v105, v2
	v_mov_b32_e32 v114, v2
	v_mov_b32_e32 v115, v2
	v_mov_b32_e32 v116, v2
	v_mov_b32_e32 v117, v2
	v_mov_b32_e32 v118, v2
	v_mov_b32_e32 v119, v2
	v_mov_b32_e32 v120, v2
	v_mov_b32_e32 v121, v2
	v_mov_b32_e32 v74, v2
	v_mov_b32_e32 v75, v2
	v_mov_b32_e32 v76, v2
	v_mov_b32_e32 v77, v2
	v_mov_b32_e32 v78, v2
	v_mov_b32_e32 v79, v2
	v_mov_b32_e32 v80, v2
	v_mov_b32_e32 v81, v2
	v_mov_b32_e32 v90, v2
	v_mov_b32_e32 v91, v2
	v_mov_b32_e32 v92, v2
	v_mov_b32_e32 v93, v2
	v_mov_b32_e32 v94, v2
	v_mov_b32_e32 v95, v2
	v_mov_b32_e32 v96, v2
	v_mov_b32_e32 v97, v2
	v_mov_b32_e32 v106, v2
	v_mov_b32_e32 v107, v2
	v_mov_b32_e32 v108, v2
	v_mov_b32_e32 v109, v2
	v_mov_b32_e32 v110, v2
	v_mov_b32_e32 v111, v2
	v_mov_b32_e32 v112, v2
	v_mov_b32_e32 v113, v2
	v_mov_b32_e32 v122, v2
	v_mov_b32_e32 v123, v2
	v_mov_b32_e32 v124, v2
	v_mov_b32_e32 v125, v2
	v_mov_b32_e32 v126, v2
	v_mov_b32_e32 v127, v2
	v_mov_b32_e32 v128, v2
	v_mov_b32_e32 v129, v2
	s_setprio 0
	.p2align 6

.LBB0_1097:
	s_ashr_i32 s19, s18, 31
	s_lshl_b64 s[20:21], s[18:19], 22
	s_add_u32 s20, s34, s20
	s_addc_u32 s21, s35, s21
	s_and_b64 s[22:23], s[0:1], exec
	s_cselect_b32 s19, s21, s27
	s_cselect_b32 s51, s20, s26
	s_ashr_i32 s17, s16, 31
	s_lshl_b64 s[22:23], s[16:17], 22
	s_add_u32 s22, s36, s22
	s_addc_u32 s23, s37, s23
	s_and_b64 s[30:31], s[0:1], exec
	s_cselect_b32 s17, s23, s29
	s_cselect_b32 s52, s22, s28
	s_add_u32 s26, s26, 0x200080
	s_addc_u32 s27, s27, 0
	s_add_u32 s53, s28, 0x100
	v_mov_b32_e32 v0, 0
	s_addc_u32 s54, s29, 0
	s_mov_b32 s55, -2
	v_mov_b32_e32 v1, v0
	v_mov_b32_e32 v2, v0
	v_mov_b32_e32 v3, v0
	v_mov_b32_e32 v4, v0
	v_mov_b32_e32 v5, v0
	v_mov_b32_e32 v6, v0
	v_mov_b32_e32 v7, v0
	v_mov_b32_e32 v12, v0
	v_mov_b32_e32 v13, v0
	v_mov_b32_e32 v14, v0
	v_mov_b32_e32 v15, v0
	v_mov_b32_e32 v20, v0
	v_mov_b32_e32 v21, v0
	v_mov_b32_e32 v22, v0
	v_mov_b32_e32 v23, v0
	v_mov_b32_e32 v32, v0
	v_mov_b32_e32 v33, v0
	v_mov_b32_e32 v34, v0
	v_mov_b32_e32 v35, v0
	v_mov_b32_e32 v36, v0
	v_mov_b32_e32 v37, v0
	v_mov_b32_e32 v38, v0
	v_mov_b32_e32 v39, v0
	v_mov_b32_e32 v48, v0
	v_mov_b32_e32 v49, v0
	v_mov_b32_e32 v50, v0
	v_mov_b32_e32 v51, v0
	v_mov_b32_e32 v52, v0
	v_mov_b32_e32 v53, v0
	v_mov_b32_e32 v54, v0
	v_mov_b32_e32 v55, v0
	v_mov_b32_e32 v8, v0
	v_mov_b32_e32 v9, v0
	v_mov_b32_e32 v10, v0
	v_mov_b32_e32 v11, v0
	v_mov_b32_e32 v16, v0
	v_mov_b32_e32 v17, v0
	v_mov_b32_e32 v18, v0
	v_mov_b32_e32 v19, v0
	v_mov_b32_e32 v24, v0
	v_mov_b32_e32 v25, v0
	v_mov_b32_e32 v26, v0
	v_mov_b32_e32 v27, v0
	v_mov_b32_e32 v28, v0
	v_mov_b32_e32 v29, v0
	v_mov_b32_e32 v30, v0
	v_mov_b32_e32 v31, v0
	v_mov_b32_e32 v40, v0
	v_mov_b32_e32 v41, v0
	v_mov_b32_e32 v42, v0
	v_mov_b32_e32 v43, v0
	v_mov_b32_e32 v44, v0
	v_mov_b32_e32 v45, v0
	v_mov_b32_e32 v46, v0
	v_mov_b32_e32 v47, v0
	v_mov_b32_e32 v56, v0
	v_mov_b32_e32 v57, v0
	v_mov_b32_e32 v58, v0
	v_mov_b32_e32 v59, v0
	v_mov_b32_e32 v60, v0
	v_mov_b32_e32 v61, v0
	v_mov_b32_e32 v62, v0
	v_mov_b32_e32 v63, v0
	v_mov_b32_e32 v64, v0
	v_mov_b32_e32 v65, v0
	v_mov_b32_e32 v66, v0
	v_mov_b32_e32 v67, v0
	v_mov_b32_e32 v68, v0
	v_mov_b32_e32 v69, v0
	v_mov_b32_e32 v70, v0
	v_mov_b32_e32 v71, v0
	v_mov_b32_e32 v80, v0
	v_mov_b32_e32 v81, v0
	v_mov_b32_e32 v82, v0
	v_mov_b32_e32 v83, v0
	v_mov_b32_e32 v84, v0
	v_mov_b32_e32 v85, v0
	v_mov_b32_e32 v86, v0
	v_mov_b32_e32 v87, v0
	v_mov_b32_e32 v96, v0
	v_mov_b32_e32 v97, v0
	v_mov_b32_e32 v98, v0
	v_mov_b32_e32 v99, v0
	v_mov_b32_e32 v100, v0
	v_mov_b32_e32 v101, v0
	v_mov_b32_e32 v102, v0
	v_mov_b32_e32 v103, v0
	v_mov_b32_e32 v112, v0
	v_mov_b32_e32 v113, v0
	v_mov_b32_e32 v114, v0
	v_mov_b32_e32 v115, v0
	v_mov_b32_e32 v116, v0
	v_mov_b32_e32 v117, v0
	v_mov_b32_e32 v118, v0
	v_mov_b32_e32 v119, v0
	v_mov_b32_e32 v72, v0
	v_mov_b32_e32 v73, v0
	v_mov_b32_e32 v74, v0
	v_mov_b32_e32 v75, v0
	v_mov_b32_e32 v76, v0
	v_mov_b32_e32 v77, v0
	v_mov_b32_e32 v78, v0
	v_mov_b32_e32 v79, v0
	v_mov_b32_e32 v88, v0
	v_mov_b32_e32 v89, v0
	v_mov_b32_e32 v90, v0
	v_mov_b32_e32 v91, v0
	v_mov_b32_e32 v92, v0
	v_mov_b32_e32 v93, v0
	v_mov_b32_e32 v94, v0
	v_mov_b32_e32 v95, v0
	v_mov_b32_e32 v104, v0
	v_mov_b32_e32 v105, v0
	v_mov_b32_e32 v106, v0
	v_mov_b32_e32 v107, v0
	v_mov_b32_e32 v108, v0
	v_mov_b32_e32 v109, v0
	v_mov_b32_e32 v110, v0
	v_mov_b32_e32 v111, v0
	v_mov_b32_e32 v120, v0
	v_mov_b32_e32 v121, v0
	v_mov_b32_e32 v122, v0
	v_mov_b32_e32 v123, v0
	v_mov_b32_e32 v124, v0
	v_mov_b32_e32 v125, v0
	v_mov_b32_e32 v126, v0
	v_mov_b32_e32 v127, v0
	s_setprio 0
	.p2align 6
